# solver wave S4 second half: Tu/Tw rows via v_pk_mul_f32 + single cvt + ds_write_b16/_d16_hi (same f32 mul, same bf16 rounding)
# speedup vs baseline: 1.0156x; 1.0156x over previous
.LBB0_615:
	s_or_b64 exec, exec, s[22:23]
	v_lshlrev_b32_e32 v3, 8, v52
	v_lshlrev_b32_e32 v4, 5, v53
	s_waitcnt lgkmcnt(0)
	v_add3_u32 v26, v146, v3, v4
	v_lshlrev_b32_e32 v2, 1, v2
	v_add3_u32 v54, v146, v2, v54
	ds_read_b128 v[2:5], v26 offset:8192
	ds_read_b128 v[6:9], v26 offset:8208
	s_waitcnt lgkmcnt(1)
	v_cvt_pk_bf16_f32 v2, v2, v3
	v_cvt_pk_bf16_f32 v3, v4, v5
	s_waitcnt lgkmcnt(0)
	v_cvt_pk_bf16_f32 v4, v6, v7
	v_cvt_pk_bf16_f32 v5, v8, v9
	ds_read_b128 v[6:9], v54 offset:16384
	ds_read_b128 v[18:21], v54 offset:16416
	ds_read_b128 v[22:25], v26 offset:8256
	ds_read_b128 v[26:29], v26 offset:8272
	s_waitcnt lgkmcnt(3)
	v_mfma_f32_32x32x16_bf16 v[2:17], v[2:5], v[6:9], 0
	s_waitcnt lgkmcnt(1)
	v_cvt_pk_bf16_f32 v22, v22, v23
	v_cvt_pk_bf16_f32 v23, v24, v25
	s_waitcnt lgkmcnt(0)
	v_cvt_pk_bf16_f32 v24, v26, v27
	v_cvt_pk_bf16_f32 v25, v28, v29
	s_nop 1
	v_mfma_f32_32x32x16_bf16 v[2:17], v[22:25], v[18:21], v[2:17]
	s_nop 11
	v_cvt_pk_bf16_f32 v2, v2, v3
	v_cvt_pk_bf16_f32 v3, v4, v5
	v_cvt_pk_bf16_f32 v4, v6, v7
	v_sub_u32_e32 v6, v54, v30
	v_add_u32_e32 v18, 0x4800, v6
	v_cvt_pk_bf16_f32 v5, v8, v9
	ds_read2_b64 v[6:9], v18 offset0:64 offset1:66
	ds_read2_b64 v[18:21], v18 offset0:68 offset1:70
	v_cvt_pk_bf16_f32 v22, v10, v11
	s_waitcnt lgkmcnt(0)
	v_lshl_add_u32 v10, v160, 2, v157
	ds_read2st64_b32 v[28:29], v10 offset1:1
	v_lshl_add_u32 v54, v160, 1, v146
	v_cvt_pk_bf16_f32 v23, v12, v13
	v_cvt_pk_bf16_f32 v24, v14, v15
	v_cvt_pk_bf16_f32 v25, v16, v17
	s_waitcnt lgkmcnt(0)
	v_mul_f32_e32 v10, 0x3fb8aa3b, v29
	v_exp_f32_e32 v10, v10
	s_nop 0
	v_mul_f32_e64 v29, v10, -v28
	v_lshl_add_u32 v10, v52, 2, v157
	ds_read2st64_b32 v[26:27], v10 offset1:1
	v_pk_mul_f32 v[10:11], v[100:101], v[28:29] op_sel:[1,0] op_sel_hi:[1,1]
	v_pk_mul_f32 v[12:13], v[100:101], v[28:29] op_sel_hi:[0,1]
	v_cvt_pk_bf16_f32 v10, v10, v11
	v_cvt_pk_bf16_f32 v12, v12, v13
	ds_write_b16 v54, v10 offset:16384
	ds_write_b16_d16_hi v54, v10 offset:25600
	ds_write_b16 v54, v12 offset:16528
	ds_write_b16_d16_hi v54, v12 offset:25744
	v_pk_mul_f32 v[14:15], v[98:99], v[28:29] op_sel:[1,0] op_sel_hi:[1,1]
	v_pk_mul_f32 v[16:17], v[98:99], v[28:29] op_sel_hi:[0,1]
	v_cvt_pk_bf16_f32 v14, v14, v15
	v_cvt_pk_bf16_f32 v16, v16, v17
	ds_write_b16 v54, v14 offset:16672
	ds_write_b16_d16_hi v54, v14 offset:25888
	ds_write_b16 v54, v16 offset:16816
	ds_write_b16_d16_hi v54, v16 offset:26032
	v_pk_mul_f32 v[10:11], v[96:97], v[28:29] op_sel:[1,0] op_sel_hi:[1,1]
	v_pk_mul_f32 v[12:13], v[96:97], v[28:29] op_sel_hi:[0,1]
	v_cvt_pk_bf16_f32 v10, v10, v11
	v_cvt_pk_bf16_f32 v12, v12, v13
	ds_write_b16 v54, v10 offset:16960
	ds_write_b16_d16_hi v54, v10 offset:26176
	ds_write_b16 v54, v12 offset:17104
	ds_write_b16_d16_hi v54, v12 offset:26320
	v_pk_mul_f32 v[14:15], v[94:95], v[28:29] op_sel:[1,0] op_sel_hi:[1,1]
	v_pk_mul_f32 v[16:17], v[94:95], v[28:29] op_sel_hi:[0,1]
	v_cvt_pk_bf16_f32 v14, v14, v15
	v_cvt_pk_bf16_f32 v16, v16, v17
	ds_write_b16 v54, v14 offset:17248
	ds_write_b16_d16_hi v54, v14 offset:26464
	ds_write_b16 v54, v16 offset:17392
	ds_write_b16_d16_hi v54, v16 offset:26608
	v_pk_mul_f32 v[10:11], v[92:93], v[28:29] op_sel:[1,0] op_sel_hi:[1,1]
	v_pk_mul_f32 v[12:13], v[92:93], v[28:29] op_sel_hi:[0,1]
	v_cvt_pk_bf16_f32 v10, v10, v11
	v_cvt_pk_bf16_f32 v12, v12, v13
	ds_write_b16 v54, v10 offset:17536
	ds_write_b16_d16_hi v54, v10 offset:26752
	ds_write_b16 v54, v12 offset:17680
	ds_write_b16_d16_hi v54, v12 offset:26896
	v_pk_mul_f32 v[14:15], v[90:91], v[28:29] op_sel:[1,0] op_sel_hi:[1,1]
	v_pk_mul_f32 v[16:17], v[90:91], v[28:29] op_sel_hi:[0,1]
	v_cvt_pk_bf16_f32 v14, v14, v15
	v_cvt_pk_bf16_f32 v16, v16, v17
	ds_write_b16 v54, v14 offset:17824
	ds_write_b16_d16_hi v54, v14 offset:27040
	ds_write_b16 v54, v16 offset:17968
	ds_write_b16_d16_hi v54, v16 offset:27184
	v_pk_mul_f32 v[10:11], v[88:89], v[28:29] op_sel:[1,0] op_sel_hi:[1,1]
	v_pk_mul_f32 v[12:13], v[88:89], v[28:29] op_sel_hi:[0,1]
	v_cvt_pk_bf16_f32 v10, v10, v11
	v_cvt_pk_bf16_f32 v12, v12, v13
	ds_write_b16 v54, v10 offset:18112
	ds_write_b16_d16_hi v54, v10 offset:27328
	ds_write_b16 v54, v12 offset:18256
	ds_write_b16_d16_hi v54, v12 offset:27472
	v_pk_mul_f32 v[14:15], v[86:87], v[28:29] op_sel:[1,0] op_sel_hi:[1,1]
	v_pk_mul_f32 v[16:17], v[86:87], v[28:29] op_sel_hi:[0,1]
	v_cvt_pk_bf16_f32 v14, v14, v15
	v_cvt_pk_bf16_f32 v16, v16, v17
	ds_write_b16 v54, v14 offset:18400
	ds_write_b16_d16_hi v54, v14 offset:27616
	ds_write_b16 v54, v16 offset:18544
	ds_write_b16_d16_hi v54, v16 offset:27760
	v_pk_mul_f32 v[10:11], v[84:85], v[28:29] op_sel:[1,0] op_sel_hi:[1,1]
	v_pk_mul_f32 v[12:13], v[84:85], v[28:29] op_sel_hi:[0,1]
	v_cvt_pk_bf16_f32 v10, v10, v11
	v_cvt_pk_bf16_f32 v12, v12, v13
	ds_write_b16 v54, v10 offset:18688
	ds_write_b16_d16_hi v54, v10 offset:27904
	ds_write_b16 v54, v12 offset:18832
	ds_write_b16_d16_hi v54, v12 offset:28048
	v_pk_mul_f32 v[14:15], v[82:83], v[28:29] op_sel:[1,0] op_sel_hi:[1,1]
	v_pk_mul_f32 v[16:17], v[82:83], v[28:29] op_sel_hi:[0,1]
	v_cvt_pk_bf16_f32 v14, v14, v15
	v_cvt_pk_bf16_f32 v16, v16, v17
	ds_write_b16 v54, v14 offset:18976
	ds_write_b16_d16_hi v54, v14 offset:28192
	ds_write_b16 v54, v16 offset:19120
	ds_write_b16_d16_hi v54, v16 offset:28336
	v_pk_mul_f32 v[10:11], v[80:81], v[28:29] op_sel:[1,0] op_sel_hi:[1,1]
	v_pk_mul_f32 v[12:13], v[80:81], v[28:29] op_sel_hi:[0,1]
	v_cvt_pk_bf16_f32 v10, v10, v11
	v_cvt_pk_bf16_f32 v12, v12, v13
	ds_write_b16 v54, v10 offset:19264
	ds_write_b16_d16_hi v54, v10 offset:28480
	ds_write_b16 v54, v12 offset:19408
	ds_write_b16_d16_hi v54, v12 offset:28624
	v_pk_mul_f32 v[14:15], v[78:79], v[28:29] op_sel:[1,0] op_sel_hi:[1,1]
	v_pk_mul_f32 v[16:17], v[78:79], v[28:29] op_sel_hi:[0,1]
	v_cvt_pk_bf16_f32 v14, v14, v15
	v_cvt_pk_bf16_f32 v16, v16, v17
	ds_write_b16 v54, v14 offset:19552
	ds_write_b16_d16_hi v54, v14 offset:28768
	ds_write_b16 v54, v16 offset:19696
	ds_write_b16_d16_hi v54, v16 offset:28912
	v_pk_mul_f32 v[10:11], v[76:77], v[28:29] op_sel:[1,0] op_sel_hi:[1,1]
	v_pk_mul_f32 v[12:13], v[76:77], v[28:29] op_sel_hi:[0,1]
	v_cvt_pk_bf16_f32 v10, v10, v11
	v_cvt_pk_bf16_f32 v12, v12, v13
	ds_write_b16 v54, v10 offset:19840
	ds_write_b16_d16_hi v54, v10 offset:29056
	ds_write_b16 v54, v12 offset:19984
	ds_write_b16_d16_hi v54, v12 offset:29200
	v_pk_mul_f32 v[14:15], v[74:75], v[28:29] op_sel:[1,0] op_sel_hi:[1,1]
	v_pk_mul_f32 v[16:17], v[74:75], v[28:29] op_sel_hi:[0,1]
	v_cvt_pk_bf16_f32 v14, v14, v15
	v_cvt_pk_bf16_f32 v16, v16, v17
	ds_write_b16 v54, v14 offset:20128
	ds_write_b16_d16_hi v54, v14 offset:29344
	ds_write_b16 v54, v16 offset:20272
	ds_write_b16_d16_hi v54, v16 offset:29488
	v_pk_mul_f32 v[10:11], v[72:73], v[28:29] op_sel:[1,0] op_sel_hi:[1,1]
	v_pk_mul_f32 v[12:13], v[72:73], v[28:29] op_sel_hi:[0,1]
	v_cvt_pk_bf16_f32 v10, v10, v11
	v_cvt_pk_bf16_f32 v12, v12, v13
	ds_write_b16 v54, v10 offset:20416
	ds_write_b16_d16_hi v54, v10 offset:29632
	ds_write_b16 v54, v12 offset:20560
	ds_write_b16_d16_hi v54, v12 offset:29776
	v_pk_mul_f32 v[14:15], v[70:71], v[28:29] op_sel:[1,0] op_sel_hi:[1,1]
	v_pk_mul_f32 v[16:17], v[70:71], v[28:29] op_sel_hi:[0,1]
	v_cvt_pk_bf16_f32 v14, v14, v15
	v_cvt_pk_bf16_f32 v16, v16, v17
	ds_write_b16 v54, v14 offset:20704
	ds_write_b16_d16_hi v54, v14 offset:29920
	ds_write_b16 v54, v16 offset:20848
	ds_write_b16_d16_hi v54, v16 offset:30064
	v_mfma_f32_32x32x16_bf16 v[2:17], v[6:9], v[2:5], 0
	v_mfma_f32_32x32x16_bf16 v[2:17], v[18:21], v[22:25], v[2:17]
	s_and_saveexec_b64 s[22:23], vcc
	s_cbranch_execz .LBB0_617
	v_pk_mul_f32 v[18:19], v[32:33], v[28:29] op_sel_hi:[0,1]
	v_pk_mul_f32 v[20:21], v[30:31], v[28:29] op_sel:[1,0] op_sel_hi:[1,1]
	v_cvt_pk_bf16_f32 v18, v18, v19
	v_cvt_pk_bf16_f32 v20, v20, v21
	ds_write_b16 v54, v18 offset:20992
	ds_write_b16_d16_hi v54, v18 offset:30208
	ds_write_b16 v54, v20 offset:21136
	ds_write_b16_d16_hi v54, v20 offset:30352
	v_pk_mul_f32 v[22:23], v[32:33], v[28:29] op_sel:[1,0] op_sel_hi:[1,1]
	v_pk_mul_f32 v[24:25], v[34:35], v[28:29] op_sel_hi:[0,1]
	v_cvt_pk_bf16_f32 v22, v22, v23
	v_cvt_pk_bf16_f32 v24, v24, v25
	ds_write_b16 v54, v22 offset:21280
	ds_write_b16_d16_hi v54, v22 offset:30496
	ds_write_b16 v54, v24 offset:21424
	ds_write_b16_d16_hi v54, v24 offset:30640
	v_pk_mul_f32 v[18:19], v[34:35], v[28:29] op_sel:[1,0] op_sel_hi:[1,1]
	v_pk_mul_f32 v[20:21], v[36:37], v[28:29] op_sel_hi:[0,1]
	v_cvt_pk_bf16_f32 v18, v18, v19
	v_cvt_pk_bf16_f32 v20, v20, v21
	ds_write_b16 v54, v18 offset:21568
	ds_write_b16_d16_hi v54, v18 offset:30784
	ds_write_b16 v54, v20 offset:21712
	ds_write_b16_d16_hi v54, v20 offset:30928
	v_pk_mul_f32 v[22:23], v[36:37], v[28:29] op_sel:[1,0] op_sel_hi:[1,1]
	v_pk_mul_f32 v[24:25], v[38:39], v[28:29] op_sel_hi:[0,1]
	v_cvt_pk_bf16_f32 v22, v22, v23
	v_cvt_pk_bf16_f32 v24, v24, v25
	ds_write_b16 v54, v22 offset:21856
	ds_write_b16_d16_hi v54, v22 offset:31072
	ds_write_b16 v54, v24 offset:22000
	ds_write_b16_d16_hi v54, v24 offset:31216
	v_pk_mul_f32 v[18:19], v[38:39], v[28:29] op_sel:[1,0] op_sel_hi:[1,1]
	v_pk_mul_f32 v[20:21], v[40:41], v[28:29] op_sel_hi:[0,1]
	v_cvt_pk_bf16_f32 v18, v18, v19
	v_cvt_pk_bf16_f32 v20, v20, v21
	ds_write_b16 v54, v18 offset:22144
	ds_write_b16_d16_hi v54, v18 offset:31360
	ds_write_b16 v54, v20 offset:22288
	ds_write_b16_d16_hi v54, v20 offset:31504
	v_pk_mul_f32 v[22:23], v[40:41], v[28:29] op_sel:[1,0] op_sel_hi:[1,1]
	v_pk_mul_f32 v[24:25], v[42:43], v[28:29] op_sel_hi:[0,1]
	v_cvt_pk_bf16_f32 v22, v22, v23
	v_cvt_pk_bf16_f32 v24, v24, v25
	ds_write_b16 v54, v22 offset:22432
	ds_write_b16_d16_hi v54, v22 offset:31648
	ds_write_b16 v54, v24 offset:22576
	ds_write_b16_d16_hi v54, v24 offset:31792
	v_pk_mul_f32 v[18:19], v[42:43], v[28:29] op_sel:[1,0] op_sel_hi:[1,1]
	v_pk_mul_f32 v[20:21], v[44:45], v[28:29] op_sel_hi:[0,1]
	v_cvt_pk_bf16_f32 v18, v18, v19
	v_cvt_pk_bf16_f32 v20, v20, v21
	ds_write_b16 v54, v18 offset:22720
	ds_write_b16_d16_hi v54, v18 offset:31936
	ds_write_b16 v54, v20 offset:22864
	ds_write_b16_d16_hi v54, v20 offset:32080
	v_pk_mul_f32 v[22:23], v[44:45], v[28:29] op_sel:[1,0] op_sel_hi:[1,1]
	v_pk_mul_f32 v[24:25], v[48:49], v[28:29] op_sel_hi:[0,1]
	v_cvt_pk_bf16_f32 v22, v22, v23
	v_cvt_pk_bf16_f32 v24, v24, v25
	ds_write_b16 v54, v22 offset:23008
	ds_write_b16_d16_hi v54, v22 offset:32224
	ds_write_b16 v54, v24 offset:23152
	ds_write_b16_d16_hi v54, v24 offset:32368
	v_pk_mul_f32 v[18:19], v[48:49], v[28:29] op_sel:[1,0] op_sel_hi:[1,1]
	v_pk_mul_f32 v[20:21], v[54:55], v[28:29] op_sel:[1,0] op_sel_hi:[1,1]
	v_cvt_pk_bf16_f32 v18, v18, v19
	v_cvt_pk_bf16_f32 v20, v20, v21
	ds_write_b16 v54, v18 offset:23296
	ds_write_b16_d16_hi v54, v18 offset:32512
	ds_write_b16 v54, v20 offset:23440
	ds_write_b16_d16_hi v54, v20 offset:32656
	v_pk_mul_f32 v[22:23], v[56:57], v[28:29] op_sel_hi:[0,1]
	v_pk_mul_f32 v[24:25], v[56:57], v[28:29] op_sel:[1,0] op_sel_hi:[1,1]
	v_cvt_pk_bf16_f32 v22, v22, v23
	v_cvt_pk_bf16_f32 v24, v24, v25
	ds_write_b16 v54, v22 offset:23584
	ds_write_b16_d16_hi v54, v22 offset:32800
	ds_write_b16 v54, v24 offset:23728
	ds_write_b16_d16_hi v54, v24 offset:32944
	v_pk_mul_f32 v[18:19], v[58:59], v[28:29] op_sel_hi:[0,1]
	v_pk_mul_f32 v[20:21], v[58:59], v[28:29] op_sel:[1,0] op_sel_hi:[1,1]
	v_cvt_pk_bf16_f32 v18, v18, v19
	v_cvt_pk_bf16_f32 v20, v20, v21
	ds_write_b16 v54, v18 offset:23872
	ds_write_b16_d16_hi v54, v18 offset:33088
	ds_write_b16 v54, v20 offset:24016
	ds_write_b16_d16_hi v54, v20 offset:33232
	v_pk_mul_f32 v[22:23], v[60:61], v[28:29] op_sel_hi:[0,1]
	v_pk_mul_f32 v[24:25], v[60:61], v[28:29] op_sel:[1,0] op_sel_hi:[1,1]
	v_cvt_pk_bf16_f32 v22, v22, v23
	v_cvt_pk_bf16_f32 v24, v24, v25
	ds_write_b16 v54, v22 offset:24160
	ds_write_b16_d16_hi v54, v22 offset:33376
	ds_write_b16 v54, v24 offset:24304
	ds_write_b16_d16_hi v54, v24 offset:33520
	v_pk_mul_f32 v[18:19], v[62:63], v[28:29] op_sel_hi:[0,1]
	v_pk_mul_f32 v[20:21], v[62:63], v[28:29] op_sel:[1,0] op_sel_hi:[1,1]
	v_cvt_pk_bf16_f32 v18, v18, v19
	v_cvt_pk_bf16_f32 v20, v20, v21
	ds_write_b16 v54, v18 offset:24448
	ds_write_b16_d16_hi v54, v18 offset:33664
	ds_write_b16 v54, v20 offset:24592
	ds_write_b16_d16_hi v54, v20 offset:33808
	v_pk_mul_f32 v[22:23], v[64:65], v[28:29] op_sel_hi:[0,1]
	v_pk_mul_f32 v[24:25], v[64:65], v[28:29] op_sel:[1,0] op_sel_hi:[1,1]
	v_cvt_pk_bf16_f32 v22, v22, v23
	v_cvt_pk_bf16_f32 v24, v24, v25
	ds_write_b16 v54, v22 offset:24736
	ds_write_b16_d16_hi v54, v22 offset:33952
	ds_write_b16 v54, v24 offset:24880
	ds_write_b16_d16_hi v54, v24 offset:34096
	v_pk_mul_f32 v[18:19], v[66:67], v[28:29] op_sel_hi:[0,1]
	v_pk_mul_f32 v[20:21], v[66:67], v[28:29] op_sel:[1,0] op_sel_hi:[1,1]
	v_cvt_pk_bf16_f32 v18, v18, v19
	v_cvt_pk_bf16_f32 v20, v20, v21
	ds_write_b16 v54, v18 offset:25024
	ds_write_b16_d16_hi v54, v18 offset:34240
	ds_write_b16 v54, v20 offset:25168
	ds_write_b16_d16_hi v54, v20 offset:34384
	v_pk_mul_f32 v[22:23], v[68:69], v[28:29] op_sel_hi:[0,1]
	v_pk_mul_f32 v[24:25], v[68:69], v[28:29] op_sel:[1,0] op_sel_hi:[1,1]
	v_cvt_pk_bf16_f32 v22, v22, v23
	v_cvt_pk_bf16_f32 v24, v24, v25
	ds_write_b16 v54, v22 offset:25312
	ds_write_b16_d16_hi v54, v22 offset:34528
	ds_write_b16 v54, v24 offset:25456
	ds_write_b16_d16_hi v54, v24 offset:34672
.LBB0_617:
	s_or_b64 exec, exec, s[22:23]
	s_waitcnt lgkmcnt(14)
	v_mul_f32_e32 v18, 0x3fb8aa3b, v27
	v_exp_f32_e32 v18, v18
	v_mul_u32_u24_e32 v21, 0x120, v53
	v_or_b32_e32 v21, v21, v52
	v_lshl_add_u32 v21, v21, 1, v146
	s_nop 4
	v_mul_f32_e64 v27, v18, -v26
	s_nop 0
	v_pk_mul_f32 v[18:19], v[2:3], v[26:27] op_sel_hi:[0,1] neg_lo:[1,0] neg_hi:[1,0]
	v_pk_mul_f32 v[22:23], v[2:3], v[26:27] op_sel:[1,0] op_sel_hi:[1,1] neg_lo:[1,0] neg_hi:[1,0]
	v_cvt_pk_bf16_f32 v18, v18, v19
	v_cvt_pk_bf16_f32 v22, v22, v23
	ds_write_b16 v21, v18 offset:20992
	ds_write_b16_d16_hi v21, v18 offset:30208
	ds_write_b16 v21, v22 offset:21136
	ds_write_b16_d16_hi v21, v22 offset:30352
	v_pk_mul_f32 v[24:25], v[4:5], v[26:27] op_sel_hi:[0,1] neg_lo:[1,0] neg_hi:[1,0]
	v_pk_mul_f32 v[28:29], v[4:5], v[26:27] op_sel:[1,0] op_sel_hi:[1,1] neg_lo:[1,0] neg_hi:[1,0]
	v_cvt_pk_bf16_f32 v24, v24, v25
	v_cvt_pk_bf16_f32 v28, v28, v29
	ds_write_b16 v21, v24 offset:21280
	ds_write_b16_d16_hi v21, v24 offset:30496
	ds_write_b16 v21, v28 offset:21424
	ds_write_b16_d16_hi v21, v28 offset:30640
	v_pk_mul_f32 v[18:19], v[6:7], v[26:27] op_sel_hi:[0,1] neg_lo:[1,0] neg_hi:[1,0]
	v_pk_mul_f32 v[22:23], v[6:7], v[26:27] op_sel:[1,0] op_sel_hi:[1,1] neg_lo:[1,0] neg_hi:[1,0]
	v_cvt_pk_bf16_f32 v18, v18, v19
	v_cvt_pk_bf16_f32 v22, v22, v23
	ds_write_b16 v21, v18 offset:22144
	ds_write_b16_d16_hi v21, v18 offset:31360
	ds_write_b16 v21, v22 offset:22288
	ds_write_b16_d16_hi v21, v22 offset:31504
	v_pk_mul_f32 v[24:25], v[8:9], v[26:27] op_sel_hi:[0,1] neg_lo:[1,0] neg_hi:[1,0]
	v_pk_mul_f32 v[28:29], v[8:9], v[26:27] op_sel:[1,0] op_sel_hi:[1,1] neg_lo:[1,0] neg_hi:[1,0]
	v_cvt_pk_bf16_f32 v24, v24, v25
	v_cvt_pk_bf16_f32 v28, v28, v29
	ds_write_b16 v21, v24 offset:22432
	ds_write_b16_d16_hi v21, v24 offset:31648
	ds_write_b16 v21, v28 offset:22576
	ds_write_b16_d16_hi v21, v28 offset:31792
	v_pk_mul_f32 v[18:19], v[10:11], v[26:27] op_sel_hi:[0,1] neg_lo:[1,0] neg_hi:[1,0]
	v_pk_mul_f32 v[22:23], v[10:11], v[26:27] op_sel:[1,0] op_sel_hi:[1,1] neg_lo:[1,0] neg_hi:[1,0]
	v_cvt_pk_bf16_f32 v18, v18, v19
	v_cvt_pk_bf16_f32 v22, v22, v23
	ds_write_b16 v21, v18 offset:23296
	ds_write_b16_d16_hi v21, v18 offset:32512
	ds_write_b16 v21, v22 offset:23440
	ds_write_b16_d16_hi v21, v22 offset:32656
	v_pk_mul_f32 v[24:25], v[12:13], v[26:27] op_sel_hi:[0,1] neg_lo:[1,0] neg_hi:[1,0]
	v_pk_mul_f32 v[28:29], v[12:13], v[26:27] op_sel:[1,0] op_sel_hi:[1,1] neg_lo:[1,0] neg_hi:[1,0]
	v_cvt_pk_bf16_f32 v24, v24, v25
	v_cvt_pk_bf16_f32 v28, v28, v29
	ds_write_b16 v21, v24 offset:23584
	ds_write_b16_d16_hi v21, v24 offset:32800
	ds_write_b16 v21, v28 offset:23728
	ds_write_b16_d16_hi v21, v28 offset:32944
	v_pk_mul_f32 v[18:19], v[14:15], v[26:27] op_sel_hi:[0,1] neg_lo:[1,0] neg_hi:[1,0]
	v_pk_mul_f32 v[22:23], v[14:15], v[26:27] op_sel:[1,0] op_sel_hi:[1,1] neg_lo:[1,0] neg_hi:[1,0]
	v_cvt_pk_bf16_f32 v18, v18, v19
	v_cvt_pk_bf16_f32 v22, v22, v23
	ds_write_b16 v21, v18 offset:24448
	ds_write_b16_d16_hi v21, v18 offset:33664
	ds_write_b16 v21, v22 offset:24592
	ds_write_b16_d16_hi v21, v22 offset:33808
	v_pk_mul_f32 v[24:25], v[16:17], v[26:27] op_sel_hi:[0,1] neg_lo:[1,0] neg_hi:[1,0]
	v_pk_mul_f32 v[28:29], v[16:17], v[26:27] op_sel:[1,0] op_sel_hi:[1,1] neg_lo:[1,0] neg_hi:[1,0]
	v_cvt_pk_bf16_f32 v24, v24, v25
	v_cvt_pk_bf16_f32 v28, v28, v29
	ds_write_b16 v21, v24 offset:24736
	ds_write_b16_d16_hi v21, v24 offset:33952
	ds_write_b16 v21, v28 offset:24880
	ds_write_b16_d16_hi v21, v28 offset:34096
